# v48
# speedup vs baseline: 1.0041x; 1.0041x over previous
; #define WAIT_V(n) asm volatile("s_waitcnt vmcnt(" #n ")" ::: "memory")
; #define WAIT_L(n) asm volatile("s_waitcnt lgkmcnt(" #n ")" ::: "memory")
; #define BAR __builtin_amdgcn_s_barrier()
; #define SCHED __builtin_amdgcn_sched_barrier(0)
; template <int EPI>
; __device__ __forceinline__ void gemm_tile(const Params& p, const bf16* __restrict__ A, const bf16* __restrict__ Bt, const int K,
;                                           const int nt, const int brow, const int bcol, int pm, int pn) {
;     ...
;   for (int t = 0; t < nt - 2; t += 2) {
;     LDB(B0, 0, 0); SCHED; LDA(At, 0, 0); STAGE(SA(1, 1), A, brow + HALF, t + 1);
;     WAIT_L(8); BAR; WAIT_L(0); MMA(0, 0, At, B0); BAR; SCHED;
;     LDB(B1, 0, 1); STAGE(SB(0, 0), Bt, bcol, t + 2);
;     BAR; WAIT_L(0); MMA(0, 1, At, B1); BAR;
;     LDA(At, 0, 1); STAGE(SA(0, 0), A, brow, t + 2);
;     BAR; WAIT_L(0); MMA(1, 0, At, B0); BAR; SCHED;
;     STAGE(SB(0, 1), Bt, bcol + HALF, t + 2);
;     WAIT_V(6); BAR; MMA(1, 1, At, B1); BAR;
;     LDB(B0, 1, 0); SCHED; LDA(At, 1, 0); STAGE(SA(0, 1), A, brow + HALF, t + 2);
;     WAIT_L(8); BAR; WAIT_L(0); MMA(0, 0, At, B0); BAR; SCHED;
;     LDB(B1, 1, 1); STAGE(SB(1, 0), Bt, bcol, t + 3);
;     BAR; WAIT_L(0); MMA(0, 1, At, B1); BAR;
.LBB0_415:
	ds_read_b128 v[162:165], v160
	ds_read_b128 v[166:169], v160 offset:1024
	ds_read_b128 v[170:173], v160 offset:2048
	ds_read_b128 v[174:177], v160 offset:3072
	s_mov_b32 m0, s99
	ds_read_b128 v[178:181], v136
	ds_read_b128 v[182:185], v136 offset:1024
	ds_read_b128 v[186:189], v135
	ds_read_b128 v[190:193], v135 offset:1024
	ds_read_b128 v[194:197], v131
	ds_read_b128 v[198:201], v131 offset:1024
	ds_read_b128 v[202:205], v130
	ds_read_b128 v[208:211], v130 offset:1024
	global_load_lds_dwordx4 v[246:247], off
	s_mov_b32 m0, s98
	s_nop 0
	global_load_lds_dwordx4 v[244:245], off
	s_waitcnt lgkmcnt(8)
	s_setprio 1
	s_barrier
	s_waitcnt lgkmcnt(0)
	v_mfma_f32_16x16x32_bf16 v[124:127], v[178:181], v[162:165], v[124:127]
	v_mfma_f32_16x16x32_bf16 v[120:123], v[178:181], v[170:173], v[120:123]
	v_mfma_f32_16x16x32_bf16 v[116:119], v[186:189], v[162:165], v[116:119]
	v_mfma_f32_16x16x32_bf16 v[112:115], v[186:189], v[170:173], v[112:115]
	v_mfma_f32_16x16x32_bf16 v[108:111], v[194:197], v[162:165], v[108:111]
	v_mfma_f32_16x16x32_bf16 v[104:107], v[194:197], v[170:173], v[104:107]
	v_mfma_f32_16x16x32_bf16 v[100:103], v[202:205], v[162:165], v[100:103]
	v_mfma_f32_16x16x32_bf16 v[96:99], v[202:205], v[170:173], v[96:99]
	v_mfma_f32_16x16x32_bf16 v[124:127], v[182:185], v[166:169], v[124:127]
	v_mfma_f32_16x16x32_bf16 v[120:123], v[182:185], v[174:177], v[120:123]
	v_mfma_f32_16x16x32_bf16 v[116:119], v[190:193], v[166:169], v[116:119]
	v_mfma_f32_16x16x32_bf16 v[112:115], v[190:193], v[174:177], v[112:115]
	v_mfma_f32_16x16x32_bf16 v[108:111], v[198:201], v[166:169], v[108:111]
	v_mfma_f32_16x16x32_bf16 v[104:107], v[198:201], v[174:177], v[104:107]
	v_mfma_f32_16x16x32_bf16 v[100:103], v[208:211], v[166:169], v[100:103]
	v_mfma_f32_16x16x32_bf16 v[96:99], v[208:211], v[174:177], v[96:99]
	s_barrier
	s_setprio 0
	v_lshl_add_u64 v[230:231], s[36:37], 0, v[128:129]
	s_mov_b64 s[40:41], 0x100
	v_readfirstlane_b32 s31, v134
	v_lshl_add_u64 v[232:233], v[230:231], 0, s[40:41]
	s_mov_b32 m0, s31
	s_mov_b64 s[40:41], 0x40100
	v_readfirstlane_b32 s31, v137
	ds_read_b128 v[212:215], v156
	ds_read_b128 v[216:219], v156 offset:1024
	ds_read_b128 v[220:223], v156 offset:2048
	ds_read_b128 v[224:227], v156 offset:3072
	global_load_lds_dwordx4 v[232:233], off
	v_lshl_add_u64 v[232:233], v[230:231], 0, s[40:41]
	s_mov_b32 m0, s31
	s_nop 0
	global_load_lds_dwordx4 v[232:233], off
	s_mov_b64 s[40:41], 0x6202100
	v_lshl_add_u64 v[252:253], v[228:229], 0, s[40:41]
	s_mov_b64 s[40:41], 0x6242100
	v_lshl_add_u64 v[254:255], v[228:229], 0, s[40:41]
	v_lshl_add_u64 v[232:233], v[228:229], 0, s[40:41]
	v_readfirstlane_b32 s31, v138
	s_mov_b32 m0, s31
	v_readfirstlane_b32 s41, v140
	s_setprio 1
	s_barrier
	s_waitcnt lgkmcnt(0)
	v_mfma_f32_16x16x32_bf16 v[92:95], v[178:181], v[212:215], v[92:95]
	v_mfma_f32_16x16x32_bf16 v[88:91], v[178:181], v[220:223], v[88:91]
	v_mfma_f32_16x16x32_bf16 v[84:87], v[186:189], v[212:215], v[84:87]
	v_mfma_f32_16x16x32_bf16 v[80:83], v[186:189], v[220:223], v[80:83]
	v_mfma_f32_16x16x32_bf16 v[76:79], v[194:197], v[212:215], v[76:79]
	v_mfma_f32_16x16x32_bf16 v[72:75], v[194:197], v[220:223], v[72:75]
	v_mfma_f32_16x16x32_bf16 v[68:71], v[202:205], v[212:215], v[68:71]
	v_mfma_f32_16x16x32_bf16 v[64:67], v[202:205], v[220:223], v[64:67]
	v_mfma_f32_16x16x32_bf16 v[92:95], v[182:185], v[216:219], v[92:95]
	v_mfma_f32_16x16x32_bf16 v[88:91], v[182:185], v[224:227], v[88:91]
	v_mfma_f32_16x16x32_bf16 v[84:87], v[190:193], v[216:219], v[84:87]
	v_mfma_f32_16x16x32_bf16 v[80:83], v[190:193], v[224:227], v[80:83]
	v_mfma_f32_16x16x32_bf16 v[76:79], v[198:201], v[216:219], v[76:79]
	v_mfma_f32_16x16x32_bf16 v[72:75], v[198:201], v[224:227], v[72:75]
	v_mfma_f32_16x16x32_bf16 v[68:71], v[208:211], v[216:219], v[68:71]
	v_mfma_f32_16x16x32_bf16 v[64:67], v[208:211], v[224:227], v[64:67]
	s_barrier
	s_setprio 0
	ds_read_b128 v[178:181], v136 offset:16384
	ds_read_b128 v[182:185], v136 offset:17408
	ds_read_b128 v[186:189], v135 offset:16384
	ds_read_b128 v[190:193], v135 offset:17408
	ds_read_b128 v[194:197], v131 offset:16384
	ds_read_b128 v[198:201], v131 offset:17408
	ds_read_b128 v[202:205], v130 offset:16384
	ds_read_b128 v[208:211], v130 offset:17408
	global_load_lds_dwordx4 v[252:253], off
	s_mov_b32 m0, s41
	s_nop 0
	global_load_lds_dwordx4 v[254:255], off
	s_setprio 1
	s_barrier
	s_waitcnt lgkmcnt(0)
	v_mfma_f32_16x16x32_bf16 v[60:63], v[178:181], v[162:165], v[60:63]
	v_mfma_f32_16x16x32_bf16 v[56:59], v[178:181], v[170:173], v[56:59]
	v_mfma_f32_16x16x32_bf16 v[52:55], v[186:189], v[162:165], v[52:55]
	v_mfma_f32_16x16x32_bf16 v[48:51], v[186:189], v[170:173], v[48:51]
	v_mfma_f32_16x16x32_bf16 v[44:47], v[194:197], v[162:165], v[44:47]
	v_mfma_f32_16x16x32_bf16 v[40:43], v[194:197], v[170:173], v[40:43]
	v_mfma_f32_16x16x32_bf16 v[36:39], v[202:205], v[162:165], v[36:39]
	v_mfma_f32_16x16x32_bf16 v[32:35], v[202:205], v[170:173], v[32:35]
	v_mfma_f32_16x16x32_bf16 v[60:63], v[182:185], v[166:169], v[60:63]
	v_mfma_f32_16x16x32_bf16 v[56:59], v[182:185], v[174:177], v[56:59]
	v_mfma_f32_16x16x32_bf16 v[52:55], v[190:193], v[166:169], v[52:55]
	v_mfma_f32_16x16x32_bf16 v[48:51], v[190:193], v[174:177], v[48:51]
	v_mfma_f32_16x16x32_bf16 v[44:47], v[198:201], v[166:169], v[44:47]
	v_mfma_f32_16x16x32_bf16 v[40:43], v[198:201], v[174:177], v[40:43]
	v_mfma_f32_16x16x32_bf16 v[36:39], v[208:211], v[166:169], v[36:39]
	v_mfma_f32_16x16x32_bf16 v[32:35], v[208:211], v[174:177], v[32:35]
	s_barrier
; #define WAIT_V(n) asm volatile("s_waitcnt vmcnt(" #n ")" ::: "memory")
; #define WAIT_L(n) asm volatile("s_waitcnt lgkmcnt(" #n ")" ::: "memory")
; #define BAR __builtin_amdgcn_s_barrier()
; #define SCHED __builtin_amdgcn_sched_barrier(0)
; template <int EPI>
; __device__ __forceinline__ void gemm_tile(const Params& p, const bf16* __restrict__ A, const bf16* __restrict__ Bt, const int K,
;                                           const int nt, const int brow, const int bcol, int pm, int pn) {
;     ...
;     STAGE(SB(0, 1), Bt, bcol + HALF, t + 2);
;     WAIT_V(6); BAR; MMA(1, 1, At, B1); BAR;
;     LDB(B0, 1, 0); SCHED; LDA(At, 1, 0); STAGE(SA(0, 1), A, brow + HALF, t + 2);
;     WAIT_L(8); BAR; WAIT_L(0); MMA(0, 0, At, B0); BAR; SCHED;
;     LDB(B1, 1, 1); STAGE(SB(1, 0), Bt, bcol, t + 3);
;     BAR; WAIT_L(0); MMA(0, 1, At, B1); BAR;
	s_setprio 0
	s_add_i32 s9, s9, 2
	s_add_u32 s38, s38, 0x100
	s_addc_u32 s39, s39, 0
	s_add_u32 s36, s36, 0x100
	s_addc_u32 s37, s37, 0
	s_mov_b64 s[40:41], 0x80100
	v_readfirstlane_b32 s31, v141
	v_lshl_add_u64 v[162:163], v[230:231], 0, s[40:41]
	s_mov_b32 m0, s31
	s_mov_b64 s[40:41], 0xc0100
	v_readfirstlane_b32 s31, v147
	global_load_lds_dwordx4 v[162:163], off
	v_lshl_add_u64 v[162:163], v[230:231], 0, s[40:41]
	s_mov_b32 m0, s31
	s_nop 0
	global_load_lds_dwordx4 v[162:163], off
	s_mov_b64 s[40:41], 0x6282100
	v_lshl_add_u64 v[248:249], v[228:229], 0, s[40:41]
	s_mov_b64 s[40:41], 0x62c2100
	v_lshl_add_u64 v[250:251], v[228:229], 0, s[40:41]
	s_waitcnt vmcnt(6)
	s_setprio 1
	s_barrier
	v_mfma_f32_16x16x32_bf16 v[28:31], v[178:181], v[212:215], v[28:31]
	v_mfma_f32_16x16x32_bf16 v[24:27], v[178:181], v[220:223], v[24:27]
	v_mfma_f32_16x16x32_bf16 v[20:23], v[186:189], v[212:215], v[20:23]
	v_mfma_f32_16x16x32_bf16 v[16:19], v[186:189], v[220:223], v[16:19]
	v_mfma_f32_16x16x32_bf16 v[12:15], v[194:197], v[212:215], v[12:15]
	v_mfma_f32_16x16x32_bf16 v[8:11], v[194:197], v[220:223], v[8:11]
	v_mfma_f32_16x16x32_bf16 v[4:7], v[202:205], v[212:215], v[4:7]
	v_mfma_f32_16x16x32_bf16 v[0:3], v[202:205], v[220:223], v[0:3]
	v_mfma_f32_16x16x32_bf16 v[28:31], v[182:185], v[216:219], v[28:31]
	v_mfma_f32_16x16x32_bf16 v[24:27], v[182:185], v[224:227], v[24:27]
	v_mfma_f32_16x16x32_bf16 v[20:23], v[190:193], v[216:219], v[20:23]
	v_mfma_f32_16x16x32_bf16 v[16:19], v[190:193], v[224:227], v[16:19]
	v_mfma_f32_16x16x32_bf16 v[12:15], v[198:201], v[216:219], v[12:15]
	v_mfma_f32_16x16x32_bf16 v[8:11], v[198:201], v[224:227], v[8:11]
	v_mfma_f32_16x16x32_bf16 v[4:7], v[208:211], v[216:219], v[4:7]
	v_mfma_f32_16x16x32_bf16 v[0:3], v[208:211], v[224:227], v[0:3]
	s_barrier
	s_setprio 0
	ds_read_b128 v[162:165], v149
	ds_read_b128 v[166:169], v149 offset:1024
	ds_read_b128 v[170:173], v149 offset:2048
	ds_read_b128 v[174:177], v149 offset:3072
	s_mov_b32 m0, s100
	ds_read_b128 v[178:181], v136 offset:32768
	ds_read_b128 v[182:185], v136 offset:33792
	ds_read_b128 v[186:189], v135 offset:32768
	ds_read_b128 v[190:193], v135 offset:33792
	ds_read_b128 v[194:197], v131 offset:32768
	ds_read_b128 v[198:201], v131 offset:33792
	ds_read_b128 v[202:205], v130 offset:32768
	ds_read_b128 v[208:211], v130 offset:33792
	global_load_lds_dwordx4 v[248:249], off
	s_mov_b32 m0, s101
	s_nop 0
	global_load_lds_dwordx4 v[250:251], off
	s_waitcnt lgkmcnt(8)
	s_setprio 1
	s_barrier
	s_waitcnt lgkmcnt(0)
	v_mfma_f32_16x16x32_bf16 v[124:127], v[178:181], v[162:165], v[124:127]
	v_mfma_f32_16x16x32_bf16 v[120:123], v[178:181], v[170:173], v[120:123]
	v_mfma_f32_16x16x32_bf16 v[116:119], v[186:189], v[162:165], v[116:119]
	v_mfma_f32_16x16x32_bf16 v[112:115], v[186:189], v[170:173], v[112:115]
	v_mfma_f32_16x16x32_bf16 v[108:111], v[194:197], v[162:165], v[108:111]
	v_mfma_f32_16x16x32_bf16 v[104:107], v[194:197], v[170:173], v[104:107]
	v_mfma_f32_16x16x32_bf16 v[100:103], v[202:205], v[162:165], v[100:103]
	v_mfma_f32_16x16x32_bf16 v[96:99], v[202:205], v[170:173], v[96:99]
	v_mfma_f32_16x16x32_bf16 v[124:127], v[182:185], v[166:169], v[124:127]
	v_mfma_f32_16x16x32_bf16 v[120:123], v[182:185], v[174:177], v[120:123]
	v_mfma_f32_16x16x32_bf16 v[116:119], v[190:193], v[166:169], v[116:119]
	v_mfma_f32_16x16x32_bf16 v[112:115], v[190:193], v[174:177], v[112:115]
	v_mfma_f32_16x16x32_bf16 v[108:111], v[198:201], v[166:169], v[108:111]
	v_mfma_f32_16x16x32_bf16 v[104:107], v[198:201], v[174:177], v[104:107]
	v_mfma_f32_16x16x32_bf16 v[100:103], v[208:211], v[166:169], v[100:103]
	v_mfma_f32_16x16x32_bf16 v[96:99], v[208:211], v[174:177], v[96:99]
	s_barrier
	s_setprio 0
	s_mov_b64 s[40:41], 0x180
	v_readfirstlane_b32 s31, v151
	v_lshl_add_u64 v[232:233], v[230:231], 0, s[40:41]
	s_mov_b32 m0, s31
	s_mov_b64 s[40:41], 0x40180
	v_readfirstlane_b32 s31, v152
	ds_read_b128 v[212:215], v139
	ds_read_b128 v[216:219], v139 offset:1024
	ds_read_b128 v[220:223], v139 offset:2048
	ds_read_b128 v[224:227], v139 offset:3072
	global_load_lds_dwordx4 v[232:233], off
	v_lshl_add_u64 v[232:233], v[230:231], 0, s[40:41]
	s_mov_b32 m0, s31
	s_nop 0
	global_load_lds_dwordx4 v[232:233], off
	s_mov_b64 s[40:41], 0x6202180
	v_lshl_add_u64 v[252:253], v[228:229], 0, s[40:41]
	v_lshl_add_u64 v[232:233], v[228:229], 0, s[40:41]
	s_mov_b64 s[40:41], 0x6242180
	v_lshl_add_u64 v[254:255], v[228:229], 0, s[40:41]
	v_lshl_add_u64 v[228:229], v[228:229], 0, s[40:41]
	v_readfirstlane_b32 s31, v153
	s_mov_b32 m0, s31
	v_readfirstlane_b32 s41, v154
	s_setprio 1
	s_barrier
	s_waitcnt lgkmcnt(0)
	v_mfma_f32_16x16x32_bf16 v[92:95], v[178:181], v[212:215], v[92:95]
	v_mfma_f32_16x16x32_bf16 v[88:91], v[178:181], v[220:223], v[88:91]
	v_mfma_f32_16x16x32_bf16 v[84:87], v[186:189], v[212:215], v[84:87]
	v_mfma_f32_16x16x32_bf16 v[80:83], v[186:189], v[220:223], v[80:83]
	v_mfma_f32_16x16x32_bf16 v[76:79], v[194:197], v[212:215], v[76:79]
	v_mfma_f32_16x16x32_bf16 v[72:75], v[194:197], v[220:223], v[72:75]
	v_mfma_f32_16x16x32_bf16 v[68:71], v[202:205], v[212:215], v[68:71]
	v_mfma_f32_16x16x32_bf16 v[64:67], v[202:205], v[220:223], v[64:67]
	v_mfma_f32_16x16x32_bf16 v[92:95], v[182:185], v[216:219], v[92:95]
	v_mfma_f32_16x16x32_bf16 v[88:91], v[182:185], v[224:227], v[88:91]
	v_mfma_f32_16x16x32_bf16 v[84:87], v[190:193], v[216:219], v[84:87]
	v_mfma_f32_16x16x32_bf16 v[80:83], v[190:193], v[224:227], v[80:83]
	v_mfma_f32_16x16x32_bf16 v[76:79], v[198:201], v[216:219], v[76:79]
	v_mfma_f32_16x16x32_bf16 v[72:75], v[198:201], v[224:227], v[72:75]
	v_mfma_f32_16x16x32_bf16 v[68:71], v[208:211], v[216:219], v[68:71]
	v_mfma_f32_16x16x32_bf16 v[64:67], v[208:211], v[224:227], v[64:67]
	s_barrier
; #define WAIT_V(n) asm volatile("s_waitcnt vmcnt(" #n ")" ::: "memory")
; #define WAIT_L(n) asm volatile("s_waitcnt lgkmcnt(" #n ")" ::: "memory")
; #define BAR __builtin_amdgcn_s_barrier()
; #define SCHED __builtin_amdgcn_sched_barrier(0)
; template <int EPI>
; __device__ __forceinline__ void gemm_tile(const Params& p, const bf16* __restrict__ A, const bf16* __restrict__ Bt, const int K,
;                                           const int nt, const int brow, const int bcol, int pm, int pn) {
;     ...
;     LDA(At, 1, 1); STAGE(SA(1, 0), A, brow, t + 3);
;     BAR; WAIT_L(0); MMA(1, 0, At, B0); BAR; SCHED;
;     STAGE(SB(1, 1), Bt, bcol + HALF, t + 3);
;     WAIT_V(6); BAR; MMA(1, 1, At, B1); BAR;
;   }
;   { LDB(B0, 0, 0); LDA(At, 0, 0); STAGE(SA(1, 1), A, brow + HALF, nt - 1);
;     BAR; WAIT_L(0); MMA(0, 0, At, B0); BAR;
	s_setprio 0
	ds_read_b128 v[178:181], v136 offset:49152
	ds_read_b128 v[182:185], v136 offset:50176
	ds_read_b128 v[186:189], v135 offset:49152
	ds_read_b128 v[190:193], v135 offset:50176
	ds_read_b128 v[194:197], v131 offset:49152
	ds_read_b128 v[198:201], v131 offset:50176
	ds_read_b128 v[202:205], v130 offset:49152
	ds_read_b128 v[208:211], v130 offset:50176
	global_load_lds_dwordx4 v[252:253], off
	s_mov_b32 m0, s41
	s_nop 0
	global_load_lds_dwordx4 v[254:255], off
	s_setprio 1
	s_barrier
	s_waitcnt lgkmcnt(0)
	v_mfma_f32_16x16x32_bf16 v[60:63], v[178:181], v[162:165], v[60:63]
	v_mfma_f32_16x16x32_bf16 v[56:59], v[178:181], v[170:173], v[56:59]
	v_mfma_f32_16x16x32_bf16 v[52:55], v[186:189], v[162:165], v[52:55]
	v_mfma_f32_16x16x32_bf16 v[48:51], v[186:189], v[170:173], v[48:51]
	v_mfma_f32_16x16x32_bf16 v[44:47], v[194:197], v[162:165], v[44:47]
	v_mfma_f32_16x16x32_bf16 v[40:43], v[194:197], v[170:173], v[40:43]
	v_mfma_f32_16x16x32_bf16 v[36:39], v[202:205], v[162:165], v[36:39]
	v_mfma_f32_16x16x32_bf16 v[32:35], v[202:205], v[170:173], v[32:35]
	v_mfma_f32_16x16x32_bf16 v[60:63], v[182:185], v[166:169], v[60:63]
	v_mfma_f32_16x16x32_bf16 v[56:59], v[182:185], v[174:177], v[56:59]
	v_mfma_f32_16x16x32_bf16 v[52:55], v[190:193], v[166:169], v[52:55]
	v_mfma_f32_16x16x32_bf16 v[48:51], v[190:193], v[174:177], v[48:51]
	v_mfma_f32_16x16x32_bf16 v[44:47], v[198:201], v[166:169], v[44:47]
	v_mfma_f32_16x16x32_bf16 v[40:43], v[198:201], v[174:177], v[40:43]
	v_mfma_f32_16x16x32_bf16 v[36:39], v[208:211], v[166:169], v[36:39]
	v_mfma_f32_16x16x32_bf16 v[32:35], v[208:211], v[174:177], v[32:35]
	s_barrier
	s_setprio 0
	s_mov_b64 s[40:41], 0x80180
	v_readfirstlane_b32 s31, v155
	v_lshl_add_u64 v[162:163], v[230:231], 0, s[40:41]
	s_mov_b32 m0, s31
	s_mov_b64 s[40:41], 0xc0180
	v_readfirstlane_b32 s31, v157
	global_load_lds_dwordx4 v[162:163], off
	v_lshl_add_u64 v[162:163], v[230:231], 0, s[40:41]
	s_mov_b32 m0, s31
	s_nop 0
	global_load_lds_dwordx4 v[162:163], off
	v_lshl_add_u64 v[228:229], s[38:39], 0, v[128:129]
	s_mov_b64 s[40:41], 0x6282080
	v_lshl_add_u64 v[246:247], v[228:229], 0, s[40:41]
	s_mov_b64 s[40:41], 0x62c2080
	v_lshl_add_u64 v[244:245], v[228:229], 0, s[40:41]
	s_waitcnt vmcnt(6)
	s_setprio 1
	s_barrier
	v_mfma_f32_16x16x32_bf16 v[28:31], v[178:181], v[212:215], v[28:31]
	v_mfma_f32_16x16x32_bf16 v[24:27], v[178:181], v[220:223], v[24:27]
	v_mfma_f32_16x16x32_bf16 v[20:23], v[186:189], v[212:215], v[20:23]
	v_mfma_f32_16x16x32_bf16 v[16:19], v[186:189], v[220:223], v[16:19]
	v_mfma_f32_16x16x32_bf16 v[12:15], v[194:197], v[212:215], v[12:15]
	v_mfma_f32_16x16x32_bf16 v[8:11], v[194:197], v[220:223], v[8:11]
	v_mfma_f32_16x16x32_bf16 v[4:7], v[202:205], v[212:215], v[4:7]
	v_mfma_f32_16x16x32_bf16 v[0:3], v[202:205], v[220:223], v[0:3]
	v_mfma_f32_16x16x32_bf16 v[28:31], v[182:185], v[216:219], v[28:31]
	v_mfma_f32_16x16x32_bf16 v[24:27], v[182:185], v[224:227], v[24:27]
	v_mfma_f32_16x16x32_bf16 v[20:23], v[190:193], v[216:219], v[20:23]
	v_mfma_f32_16x16x32_bf16 v[16:19], v[190:193], v[224:227], v[16:19]
	v_mfma_f32_16x16x32_bf16 v[12:15], v[198:201], v[216:219], v[12:15]
	v_mfma_f32_16x16x32_bf16 v[8:11], v[198:201], v[224:227], v[8:11]
	v_mfma_f32_16x16x32_bf16 v[4:7], v[208:211], v[216:219], v[4:7]
	v_mfma_f32_16x16x32_bf16 v[0:3], v[208:211], v[224:227], v[0:3]
	s_barrier
	s_setprio 0
	s_cmp_lt_u32 s9, 28
	s_cbranch_scc1 .LBB0_415
	s_add_u32 s6, s60, s6
	s_addc_u32 s7, s61, s7
	v_lshl_add_u64 v[128:129], s[6:7], 0, v[132:133]
	v_readfirstlane_b32 s6, v159
	s_mov_b32 m0, s6
	s_add_u32 s6, s60, s34
	v_lshl_add_u64 v[128:129], v[128:129], 0, s[28:29]
	s_addc_u32 s7, s61, s35
	ds_read_b128 v[150:153], v160
	ds_read_b128 v[162:165], v160 offset:1024
	ds_read_b128 v[166:169], v160 offset:2048
	ds_read_b128 v[170:173], v160 offset:3072
	ds_read_b128 v[174:177], v136
	ds_read_b128 v[178:181], v136 offset:1024
	ds_read_b128 v[182:185], v135
	ds_read_b128 v[186:189], v135 offset:1024
	ds_read_b128 v[190:193], v131
	ds_read_b128 v[194:197], v131 offset:1024
	ds_read_b128 v[198:201], v130
	ds_read_b128 v[202:205], v130 offset:1024
	global_load_lds_dwordx4 v[128:129], off
	v_lshl_add_u64 v[128:129], s[6:7], 0, v[132:133]
	v_readfirstlane_b32 s6, v158
	v_lshl_add_u64 v[128:129], v[128:129], 0, s[28:29]
	s_mov_b32 m0, s6
	s_nop 0
	global_load_lds_dwordx4 v[128:129], off
	s_setprio 1
	s_barrier
	s_waitcnt lgkmcnt(0)
	v_mfma_f32_16x16x32_bf16 v[124:127], v[174:177], v[150:153], v[124:127]
	v_mfma_f32_16x16x32_bf16 v[120:123], v[174:177], v[166:169], v[120:123]
	v_mfma_f32_16x16x32_bf16 v[116:119], v[182:185], v[150:153], v[116:119]
	v_mfma_f32_16x16x32_bf16 v[108:111], v[190:193], v[150:153], v[108:111]
	v_mfma_f32_16x16x32_bf16 v[124:127], v[178:181], v[162:165], v[124:127]
	v_mfma_f32_16x16x32_bf16 v[120:123], v[178:181], v[170:173], v[120:123]
	v_mfma_f32_16x16x32_bf16 v[116:119], v[186:189], v[162:165], v[116:119]
	v_mfma_f32_16x16x32_bf16 v[112:115], v[182:185], v[166:169], v[112:115]
	v_mfma_f32_16x16x32_bf16 v[108:111], v[194:197], v[162:165], v[108:111]
	v_mfma_f32_16x16x32_bf16 v[104:107], v[190:193], v[166:169], v[104:107]
	v_mfma_f32_16x16x32_bf16 v[100:103], v[198:201], v[150:153], v[100:103]
	v_mfma_f32_16x16x32_bf16 v[96:99], v[198:201], v[166:169], v[96:99]
	v_mfma_f32_16x16x32_bf16 v[158:161], v[186:189], v[170:173], v[112:115]
	v_mfma_f32_16x16x32_bf16 v[208:211], v[194:197], v[170:173], v[104:107]
	v_mfma_f32_16x16x32_bf16 v[212:215], v[202:205], v[162:165], v[100:103]
	v_mfma_f32_16x16x32_bf16 v[216:219], v[202:205], v[170:173], v[96:99]
	s_barrier
; #define WAIT_V(n) asm volatile("s_waitcnt vmcnt(" #n ")" ::: "memory")
; #define WAIT_L(n) asm volatile("s_waitcnt lgkmcnt(" #n ")" ::: "memory")
; #define BAR __builtin_amdgcn_s_barrier()
; template <int EPI>
; __device__ __forceinline__ void gemm_tile(const Params& p, const bf16* __restrict__ A, const bf16* __restrict__ Bt, const int K,
;                                           const int nt, const int brow, const int bcol, int pm, int pn) {
;     ...
;     LDB(B1, 0, 1); BAR; WAIT_L(0); MMA(0, 1, At, B1); BAR;
;     LDA(At, 0, 1); WAIT_V(4); BAR; WAIT_L(0); MMA(1, 0, At, B0); MMA(1, 1, At, B1); BAR; }
;   { LDB(B0, 1, 0); LDA(At, 1, 0); WAIT_V(2); BAR; WAIT_L(0); MMA(0, 0, At, B0); BAR;
	s_setprio 0
	s_nop 1
	ds_read_b128 v[96:99], v156
	ds_read_b128 v[100:103], v156 offset:1024
	ds_read_b128 v[104:107], v156 offset:2048
	ds_read_b128 v[112:115], v156 offset:3072
	s_setprio 1
	s_barrier
	s_waitcnt lgkmcnt(0)
	v_mfma_f32_16x16x32_bf16 v[92:95], v[174:177], v[96:99], v[92:95]
	v_mfma_f32_16x16x32_bf16 v[88:91], v[174:177], v[104:107], v[88:91]
	v_mfma_f32_16x16x32_bf16 v[84:87], v[182:185], v[96:99], v[84:87]
	v_mfma_f32_16x16x32_bf16 v[76:79], v[190:193], v[96:99], v[76:79]
	v_mfma_f32_16x16x32_bf16 v[92:95], v[178:181], v[100:103], v[92:95]
	v_mfma_f32_16x16x32_bf16 v[88:91], v[178:181], v[112:115], v[88:91]
	v_mfma_f32_16x16x32_bf16 v[84:87], v[186:189], v[100:103], v[84:87]
	v_mfma_f32_16x16x32_bf16 v[80:83], v[182:185], v[104:107], v[80:83]
	v_mfma_f32_16x16x32_bf16 v[76:79], v[194:197], v[100:103], v[76:79]
	v_mfma_f32_16x16x32_bf16 v[72:75], v[190:193], v[104:107], v[72:75]
	v_mfma_f32_16x16x32_bf16 v[68:71], v[198:201], v[96:99], v[68:71]
	v_mfma_f32_16x16x32_bf16 v[64:67], v[198:201], v[104:107], v[64:67]
	v_mfma_f32_16x16x32_bf16 v[154:157], v[186:189], v[112:115], v[80:83]
	v_mfma_f32_16x16x32_bf16 v[174:177], v[194:197], v[112:115], v[72:75]
	v_mfma_f32_16x16x32_bf16 v[178:181], v[202:205], v[100:103], v[68:71]
	v_mfma_f32_16x16x32_bf16 v[182:185], v[202:205], v[112:115], v[64:67]
	s_barrier
	s_setprio 0
	s_nop 1
	ds_read_b128 v[64:67], v136 offset:16384
	ds_read_b128 v[68:71], v136 offset:17408
	ds_read_b128 v[72:75], v135 offset:16384
	ds_read_b128 v[80:83], v135 offset:17408
	ds_read_b128 v[186:189], v131 offset:16384
	ds_read_b128 v[190:193], v131 offset:17408
	ds_read_b128 v[194:197], v130 offset:16384
	ds_read_b128 v[198:201], v130 offset:17408
	s_waitcnt vmcnt(4)
	s_setprio 1
	s_barrier
	s_waitcnt lgkmcnt(0)
	v_mfma_f32_16x16x32_bf16 v[60:63], v[64:67], v[150:153], v[60:63]
	v_mfma_f32_16x16x32_bf16 v[56:59], v[64:67], v[166:169], v[56:59]
	v_mfma_f32_16x16x32_bf16 v[52:55], v[72:75], v[150:153], v[52:55]
	v_mfma_f32_16x16x32_bf16 v[44:47], v[186:189], v[150:153], v[44:47]
	v_mfma_f32_16x16x32_bf16 v[60:63], v[68:71], v[162:165], v[60:63]
	v_mfma_f32_16x16x32_bf16 v[56:59], v[68:71], v[170:173], v[56:59]
	v_mfma_f32_16x16x32_bf16 v[52:55], v[80:83], v[162:165], v[52:55]
	v_mfma_f32_16x16x32_bf16 v[48:51], v[72:75], v[166:169], v[48:51]
	v_mfma_f32_16x16x32_bf16 v[44:47], v[190:193], v[162:165], v[44:47]
	v_mfma_f32_16x16x32_bf16 v[40:43], v[186:189], v[166:169], v[40:43]
	v_mfma_f32_16x16x32_bf16 v[36:39], v[194:197], v[150:153], v[36:39]
	v_mfma_f32_16x16x32_bf16 v[32:35], v[194:197], v[166:169], v[32:35]
	v_mfma_f32_16x16x32_bf16 v[202:205], v[80:83], v[170:173], v[48:51]
	v_mfma_f32_16x16x32_bf16 v[220:223], v[190:193], v[170:173], v[40:43]
	v_mfma_f32_16x16x32_bf16 v[150:153], v[198:201], v[162:165], v[36:39]
	v_mfma_f32_16x16x32_bf16 v[162:165], v[198:201], v[170:173], v[32:35]
	s_setprio 0
	s_setprio 1
	v_mfma_f32_16x16x32_bf16 v[28:31], v[64:67], v[96:99], v[28:31]
	v_mfma_f32_16x16x32_bf16 v[24:27], v[64:67], v[104:107], v[24:27]
	v_mfma_f32_16x16x32_bf16 v[20:23], v[72:75], v[96:99], v[20:23]
	v_mfma_f32_16x16x32_bf16 v[12:15], v[186:189], v[96:99], v[12:15]
	v_mfma_f32_16x16x32_bf16 v[28:31], v[68:71], v[100:103], v[28:31]
	v_mfma_f32_16x16x32_bf16 v[24:27], v[68:71], v[112:115], v[24:27]
	v_mfma_f32_16x16x32_bf16 v[20:23], v[80:83], v[100:103], v[20:23]
	v_mfma_f32_16x16x32_bf16 v[16:19], v[72:75], v[104:107], v[16:19]
	v_mfma_f32_16x16x32_bf16 v[12:15], v[190:193], v[100:103], v[12:15]
	v_mfma_f32_16x16x32_bf16 v[8:11], v[186:189], v[104:107], v[8:11]
	v_mfma_f32_16x16x32_bf16 v[4:7], v[194:197], v[96:99], v[4:7]
	v_mfma_f32_16x16x32_bf16 v[0:3], v[194:197], v[104:107], v[0:3]
	v_mfma_f32_16x16x32_bf16 v[166:169], v[80:83], v[112:115], v[16:19]
	v_mfma_f32_16x16x32_bf16 v[170:173], v[190:193], v[112:115], v[8:11]
	v_mfma_f32_16x16x32_bf16 v[186:189], v[198:201], v[100:103], v[4:7]
	v_mfma_f32_16x16x32_bf16 v[190:193], v[198:201], v[112:115], v[0:3]
	s_barrier
	s_setprio 0
	s_nop 1
	ds_read_b128 v[0:3], v149
	ds_read_b128 v[4:7], v149 offset:1024
	ds_read_b128 v[8:11], v149 offset:2048
	ds_read_b128 v[16:19], v149 offset:3072
	ds_read_b128 v[32:35], v136 offset:32768
	ds_read_b128 v[36:39], v136 offset:33792
	ds_read_b128 v[40:43], v135 offset:32768
	ds_read_b128 v[48:51], v135 offset:33792
	ds_read_b128 v[194:197], v131 offset:32768
	ds_read_b128 v[198:201], v131 offset:33792
	ds_read_b128 v[224:227], v130 offset:32768
	ds_read_b128 v[228:231], v130 offset:33792
	s_waitcnt vmcnt(2)
	s_setprio 1
	s_barrier
; #define WAIT_V(n) asm volatile("s_waitcnt vmcnt(" #n ")" ::: "memory")
; #define WAIT_L(n) asm volatile("s_waitcnt lgkmcnt(" #n ")" ::: "memory")
; #define BAR __builtin_amdgcn_s_barrier()
; template <int EPI>
; __device__ __forceinline__ void gemm_tile(const Params& p, const bf16* __restrict__ A, const bf16* __restrict__ Bt, const int K,
;                                           const int nt, const int brow, const int bcol, int pm, int pn) {
;     ...
;   { LDB(B0, 1, 0); LDA(At, 1, 0); WAIT_V(2); BAR; WAIT_L(0); MMA(0, 0, At, B0); BAR;
;     LDB(B1, 1, 1); WAIT_V(0); BAR; WAIT_L(0); MMA(0, 1, At, B1); BAR;
;     LDA(At, 1, 1); BAR; WAIT_L(0); MMA(1, 0, At, B0); MMA(1, 1, At, B1); BAR; }
;   if (wr == 0) BAR;
	s_waitcnt lgkmcnt(0)
	v_mfma_f32_16x16x32_bf16 v[64:67], v[32:35], v[0:3], v[124:127]
	v_mfma_f32_16x16x32_bf16 v[96:99], v[36:39], v[4:7], v[64:67]
	v_mfma_f32_16x16x32_bf16 v[64:67], v[32:35], v[8:11], v[120:123]
	v_mfma_f32_16x16x32_bf16 v[112:115], v[36:39], v[16:19], v[64:67]
	v_mfma_f32_16x16x32_bf16 v[64:67], v[40:43], v[0:3], v[116:119]
	v_mfma_f32_16x16x32_bf16 v[100:103], v[48:51], v[4:7], v[64:67]
	v_mfma_f32_16x16x32_bf16 v[64:67], v[40:43], v[8:11], v[158:161]
	v_mfma_f32_16x16x32_bf16 v[116:119], v[48:51], v[16:19], v[64:67]
	v_mfma_f32_16x16x32_bf16 v[64:67], v[194:197], v[0:3], v[108:111]
	v_mfma_f32_16x16x32_bf16 v[104:107], v[198:201], v[4:7], v[64:67]
	v_mfma_f32_16x16x32_bf16 v[64:67], v[194:197], v[8:11], v[208:211]
	v_mfma_f32_16x16x32_bf16 v[120:123], v[198:201], v[16:19], v[64:67]
	v_mfma_f32_16x16x32_bf16 v[64:67], v[224:227], v[0:3], v[212:215]
	v_mfma_f32_16x16x32_bf16 v[108:111], v[228:231], v[4:7], v[64:67]
	v_mfma_f32_16x16x32_bf16 v[64:67], v[224:227], v[8:11], v[216:219]
	v_mfma_f32_16x16x32_bf16 v[124:127], v[228:231], v[16:19], v[64:67]
	s_barrier
	s_setprio 0
	ds_read_b128 v[158:161], v139
	ds_read_b128 v[208:211], v139 offset:1024
	ds_read_b128 v[212:215], v139 offset:2048
	ds_read_b128 v[138:141], v139 offset:3072
	s_waitcnt vmcnt(0)
	s_setprio 1
	s_barrier
	s_waitcnt lgkmcnt(0)
	v_mfma_f32_16x16x32_bf16 v[64:67], v[32:35], v[158:161], v[92:95]
	v_mfma_f32_16x16x32_bf16 v[32:35], v[32:35], v[212:215], v[88:91]
	v_mfma_f32_16x16x32_bf16 v[80:83], v[36:39], v[138:141], v[32:35]
	v_mfma_f32_16x16x32_bf16 v[32:35], v[40:43], v[158:161], v[84:87]
	v_mfma_f32_16x16x32_bf16 v[68:71], v[48:51], v[208:211], v[32:35]
	v_mfma_f32_16x16x32_bf16 v[32:35], v[40:43], v[212:215], v[154:157]
	v_mfma_f32_16x16x32_bf16 v[84:87], v[48:51], v[138:141], v[32:35]
	v_mfma_f32_16x16x32_bf16 v[32:35], v[194:197], v[158:161], v[76:79]
	v_mfma_f32_16x16x32_bf16 v[72:75], v[198:201], v[208:211], v[32:35]
	v_mfma_f32_16x16x32_bf16 v[32:35], v[194:197], v[212:215], v[174:177]
	v_mfma_f32_16x16x32_bf16 v[88:91], v[198:201], v[138:141], v[32:35]
	v_mfma_f32_16x16x32_bf16 v[32:35], v[224:227], v[158:161], v[178:181]
	v_mfma_f32_16x16x32_bf16 v[76:79], v[228:231], v[208:211], v[32:35]
	v_mfma_f32_16x16x32_bf16 v[32:35], v[224:227], v[212:215], v[182:185]
	v_mfma_f32_16x16x32_bf16 v[64:67], v[36:39], v[208:211], v[64:67]
	v_mfma_f32_16x16x32_bf16 v[92:95], v[228:231], v[138:141], v[32:35]
	s_barrier
	s_setprio 0
	ds_read_b128 v[154:157], v136 offset:49152
	ds_read_b128 v[174:177], v136 offset:50176
	ds_read_b128 v[178:181], v135 offset:49152
	ds_read_b128 v[134:137], v135 offset:50176
	ds_read_b128 v[182:185], v131 offset:49152
	ds_read_b128 v[194:197], v131 offset:50176
	ds_read_b128 v[198:201], v130 offset:49152
	ds_read_b128 v[128:131], v130 offset:50176
	s_setprio 1
	s_barrier
	s_waitcnt lgkmcnt(0)
	v_mfma_f32_16x16x32_bf16 v[36:39], v[154:157], v[8:11], v[56:59]
	v_mfma_f32_16x16x32_bf16 v[40:43], v[178:181], v[8:11], v[202:205]
	v_mfma_f32_16x16x32_bf16 v[32:35], v[154:157], v[0:3], v[60:63]
	v_mfma_f32_16x16x32_bf16 v[48:51], v[174:177], v[16:19], v[36:39]
	v_mfma_f32_16x16x32_bf16 v[36:39], v[178:181], v[0:3], v[52:55]
	v_mfma_f32_16x16x32_bf16 v[52:55], v[134:137], v[16:19], v[40:43]
	v_mfma_f32_16x16x32_bf16 v[40:43], v[182:185], v[0:3], v[44:47]
	v_mfma_f32_16x16x32_bf16 v[44:47], v[182:185], v[8:11], v[220:223]
	v_mfma_f32_16x16x32_bf16 v[0:3], v[198:201], v[0:3], v[150:153]
	v_mfma_f32_16x16x32_bf16 v[56:59], v[194:197], v[16:19], v[44:47]
	v_mfma_f32_16x16x32_bf16 v[44:47], v[128:131], v[4:7], v[0:3]
	v_mfma_f32_16x16x32_bf16 v[0:3], v[198:201], v[8:11], v[162:165]
	v_mfma_f32_16x16x32_bf16 v[32:35], v[174:177], v[4:7], v[32:35]
	v_mfma_f32_16x16x32_bf16 v[36:39], v[134:137], v[4:7], v[36:39]
	v_mfma_f32_16x16x32_bf16 v[40:43], v[194:197], v[4:7], v[40:43]
	v_mfma_f32_16x16x32_bf16 v[60:63], v[128:131], v[16:19], v[0:3]
	s_setprio 0
	s_setprio 1
	v_mfma_f32_16x16x32_bf16 v[4:7], v[154:157], v[212:215], v[24:27]
	v_mfma_f32_16x16x32_bf16 v[8:11], v[178:181], v[212:215], v[166:169]
	v_mfma_f32_16x16x32_bf16 v[16:19], v[174:177], v[138:141], v[4:7]
	v_mfma_f32_16x16x32_bf16 v[4:7], v[178:181], v[158:161], v[20:23]
	v_mfma_f32_16x16x32_bf16 v[20:23], v[134:137], v[138:141], v[8:11]
	v_mfma_f32_16x16x32_bf16 v[8:11], v[182:185], v[158:161], v[12:15]
	v_mfma_f32_16x16x32_bf16 v[12:15], v[182:185], v[212:215], v[170:173]
	v_mfma_f32_16x16x32_bf16 v[0:3], v[154:157], v[158:161], v[28:31]
	v_mfma_f32_16x16x32_bf16 v[24:27], v[194:197], v[138:141], v[12:15]
	v_mfma_f32_16x16x32_bf16 v[12:15], v[198:201], v[158:161], v[186:189]
	v_mfma_f32_16x16x32_bf16 v[28:31], v[198:201], v[212:215], v[190:193]
	v_mfma_f32_16x16x32_bf16 v[0:3], v[174:177], v[208:211], v[0:3]
	v_mfma_f32_16x16x32_bf16 v[4:7], v[134:137], v[208:211], v[4:7]
	v_mfma_f32_16x16x32_bf16 v[8:11], v[194:197], v[208:211], v[8:11]
	v_mfma_f32_16x16x32_bf16 v[12:15], v[128:131], v[208:211], v[12:15]
	v_mfma_f32_16x16x32_bf16 v[28:31], v[128:131], v[138:141], v[28:31]
	s_barrier
	s_setprio 0
	s_cmpk_gt_u32 s5, 0xff
	s_cbranch_scc1 .LBB0_418
	s_barrier

; #define WAIT_V(n) asm volatile("s_waitcnt vmcnt(" #n ")" ::: "memory")
; #define WAIT_L(n) asm volatile("s_waitcnt lgkmcnt(" #n ")" ::: "memory")
; #define BAR __builtin_amdgcn_s_barrier()
; #define SCHED __builtin_amdgcn_sched_barrier(0)
; template <int EPI>
; __device__ __forceinline__ void gemm_tile(const Params& p, const bf16* __restrict__ A, const bf16* __restrict__ Bt, const int K,
;                                           const int nt, const int brow, const int bcol, int pm, int pn) {
;     ...
;   for (int t = 0; t < nt - 2; t += 2) {
;     LDB(B0, 0, 0); SCHED; LDA(At, 0, 0); STAGE(SA(1, 1), A, brow + HALF, t + 1);
;     WAIT_L(8); BAR; WAIT_L(0); MMA(0, 0, At, B0); BAR; SCHED;
;     LDB(B1, 0, 1); STAGE(SB(0, 0), Bt, bcol, t + 2);
;     BAR; WAIT_L(0); MMA(0, 1, At, B1); BAR;
;     LDA(At, 0, 1); STAGE(SA(0, 0), A, brow, t + 2);
;     BAR; WAIT_L(0); MMA(1, 0, At, B0); BAR; SCHED;
;     STAGE(SB(0, 1), Bt, bcol + HALF, t + 2);
;     WAIT_V(6); BAR; MMA(1, 1, At, B1); BAR;
;     LDB(B0, 1, 0); SCHED; LDA(At, 1, 0); STAGE(SA(0, 1), A, brow + HALF, t + 2);
;     WAIT_L(8); BAR; WAIT_L(0); MMA(0, 0, At, B0); BAR; SCHED;
;     LDB(B1, 1, 1); STAGE(SB(1, 0), Bt, bcol, t + 3);
;     BAR; WAIT_L(0); MMA(0, 1, At, B1); BAR;
.LBB0_1704:
	ds_read_b128 v[158:161], v155
	ds_read_b128 v[162:165], v155 offset:1024
	ds_read_b128 v[166:169], v155 offset:2048
	ds_read_b128 v[170:173], v155 offset:3072
	s_mov_b32 m0, s99
	ds_read_b128 v[174:177], v137
	ds_read_b128 v[178:181], v137 offset:1024
	ds_read_b128 v[182:185], v136
	ds_read_b128 v[186:189], v136 offset:1024
	ds_read_b128 v[190:193], v135
	ds_read_b128 v[196:199], v135 offset:1024
	ds_read_b128 v[200:203], v133
	ds_read_b128 v[208:211], v133 offset:1024
	global_load_lds_dwordx4 v[246:247], off
	s_mov_b32 m0, s98
	s_nop 0
	global_load_lds_dwordx4 v[244:245], off
	s_waitcnt lgkmcnt(8)
	s_setprio 1
	s_barrier
	s_waitcnt lgkmcnt(0)
	v_mfma_f32_16x16x32_bf16 v[124:127], v[174:177], v[158:161], v[124:127]
	v_mfma_f32_16x16x32_bf16 v[120:123], v[174:177], v[166:169], v[120:123]
	v_mfma_f32_16x16x32_bf16 v[116:119], v[182:185], v[158:161], v[116:119]
	v_mfma_f32_16x16x32_bf16 v[112:115], v[182:185], v[166:169], v[112:115]
	v_mfma_f32_16x16x32_bf16 v[108:111], v[190:193], v[158:161], v[108:111]
	v_mfma_f32_16x16x32_bf16 v[104:107], v[190:193], v[166:169], v[104:107]
	v_mfma_f32_16x16x32_bf16 v[100:103], v[200:203], v[158:161], v[100:103]
	v_mfma_f32_16x16x32_bf16 v[96:99], v[200:203], v[166:169], v[96:99]
	v_mfma_f32_16x16x32_bf16 v[124:127], v[178:181], v[162:165], v[124:127]
	v_mfma_f32_16x16x32_bf16 v[120:123], v[178:181], v[170:173], v[120:123]
	v_mfma_f32_16x16x32_bf16 v[116:119], v[186:189], v[162:165], v[116:119]
	v_mfma_f32_16x16x32_bf16 v[112:115], v[186:189], v[170:173], v[112:115]
	v_mfma_f32_16x16x32_bf16 v[108:111], v[196:199], v[162:165], v[108:111]
	v_mfma_f32_16x16x32_bf16 v[104:107], v[196:199], v[170:173], v[104:107]
	v_mfma_f32_16x16x32_bf16 v[100:103], v[208:211], v[162:165], v[100:103]
	v_mfma_f32_16x16x32_bf16 v[96:99], v[208:211], v[170:173], v[96:99]
	s_barrier
	s_setprio 0
	v_lshl_add_u64 v[228:229], s[68:69], 0, v[130:131]
	s_mov_b64 s[84:85], 0x4c00100
	v_lshl_add_u64 v[230:231], v[228:229], 0, s[84:85]
	v_readfirstlane_b32 s84, v132
	s_mov_b32 m0, s84
	s_mov_b64 s[84:85], 0x4cb0100
	ds_read_b128 v[212:215], v151
	ds_read_b128 v[216:219], v151 offset:1024
	ds_read_b128 v[220:223], v151 offset:2048
	ds_read_b128 v[224:227], v151 offset:3072
	global_load_lds_dwordx4 v[230:231], off
	v_lshl_add_u64 v[230:231], v[228:229], 0, s[84:85]
	v_readfirstlane_b32 s84, v134
	s_mov_b32 m0, s84
	s_nop 0
	global_load_lds_dwordx4 v[230:231], off
	s_mov_b64 s[84:85], 0x12502100
	v_lshl_add_u64 v[252:253], v[204:205], 0, s[84:85]
	s_mov_b64 s[84:85], 0x125b2100
	v_lshl_add_u64 v[254:255], v[204:205], 0, s[84:85]
	v_lshl_add_u64 v[230:231], v[204:205], 0, s[84:85]
	v_readfirstlane_b32 s84, v138
	s_mov_b32 m0, s84
	v_readfirstlane_b32 s85, v139
	s_setprio 1
	s_barrier
	s_waitcnt lgkmcnt(0)
	v_mfma_f32_16x16x32_bf16 v[92:95], v[174:177], v[212:215], v[92:95]
	v_mfma_f32_16x16x32_bf16 v[88:91], v[174:177], v[220:223], v[88:91]
	v_mfma_f32_16x16x32_bf16 v[84:87], v[182:185], v[212:215], v[84:87]
	v_mfma_f32_16x16x32_bf16 v[80:83], v[182:185], v[220:223], v[80:83]
	v_mfma_f32_16x16x32_bf16 v[76:79], v[190:193], v[212:215], v[76:79]
	v_mfma_f32_16x16x32_bf16 v[72:75], v[190:193], v[220:223], v[72:75]
	v_mfma_f32_16x16x32_bf16 v[68:71], v[200:203], v[212:215], v[68:71]
	v_mfma_f32_16x16x32_bf16 v[64:67], v[200:203], v[220:223], v[64:67]
	v_mfma_f32_16x16x32_bf16 v[92:95], v[178:181], v[216:219], v[92:95]
	v_mfma_f32_16x16x32_bf16 v[88:91], v[178:181], v[224:227], v[88:91]
	v_mfma_f32_16x16x32_bf16 v[84:87], v[186:189], v[216:219], v[84:87]
	v_mfma_f32_16x16x32_bf16 v[80:83], v[186:189], v[224:227], v[80:83]
	v_mfma_f32_16x16x32_bf16 v[76:79], v[196:199], v[216:219], v[76:79]
	v_mfma_f32_16x16x32_bf16 v[72:75], v[196:199], v[224:227], v[72:75]
	v_mfma_f32_16x16x32_bf16 v[68:71], v[208:211], v[216:219], v[68:71]
	v_mfma_f32_16x16x32_bf16 v[64:67], v[208:211], v[224:227], v[64:67]
	s_barrier
	s_setprio 0
	ds_read_b128 v[174:177], v137 offset:16384
	ds_read_b128 v[178:181], v137 offset:17408
	ds_read_b128 v[182:185], v136 offset:16384
	ds_read_b128 v[186:189], v136 offset:17408
	ds_read_b128 v[190:193], v135 offset:16384
	ds_read_b128 v[196:199], v135 offset:17408
	ds_read_b128 v[200:203], v133 offset:16384
	ds_read_b128 v[208:211], v133 offset:17408
	global_load_lds_dwordx4 v[252:253], off
	s_mov_b32 m0, s85
	s_nop 0
	global_load_lds_dwordx4 v[254:255], off
	s_setprio 1
	s_barrier
	s_waitcnt lgkmcnt(0)
	v_mfma_f32_16x16x32_bf16 v[60:63], v[174:177], v[158:161], v[60:63]
	v_mfma_f32_16x16x32_bf16 v[56:59], v[174:177], v[166:169], v[56:59]
	v_mfma_f32_16x16x32_bf16 v[52:55], v[182:185], v[158:161], v[52:55]
	v_mfma_f32_16x16x32_bf16 v[48:51], v[182:185], v[166:169], v[48:51]
	v_mfma_f32_16x16x32_bf16 v[44:47], v[190:193], v[158:161], v[44:47]
	v_mfma_f32_16x16x32_bf16 v[40:43], v[190:193], v[166:169], v[40:43]
	v_mfma_f32_16x16x32_bf16 v[36:39], v[200:203], v[158:161], v[36:39]
	v_mfma_f32_16x16x32_bf16 v[32:35], v[200:203], v[166:169], v[32:35]
	v_mfma_f32_16x16x32_bf16 v[60:63], v[178:181], v[162:165], v[60:63]
	v_mfma_f32_16x16x32_bf16 v[56:59], v[178:181], v[170:173], v[56:59]
	v_mfma_f32_16x16x32_bf16 v[52:55], v[186:189], v[162:165], v[52:55]
	v_mfma_f32_16x16x32_bf16 v[48:51], v[186:189], v[170:173], v[48:51]
	v_mfma_f32_16x16x32_bf16 v[44:47], v[196:199], v[162:165], v[44:47]
	v_mfma_f32_16x16x32_bf16 v[40:43], v[196:199], v[170:173], v[40:43]
	v_mfma_f32_16x16x32_bf16 v[36:39], v[208:211], v[162:165], v[36:39]
	v_mfma_f32_16x16x32_bf16 v[32:35], v[208:211], v[170:173], v[32:35]
	s_barrier
; #define WAIT_V(n) asm volatile("s_waitcnt vmcnt(" #n ")" ::: "memory")
; #define WAIT_L(n) asm volatile("s_waitcnt lgkmcnt(" #n ")" ::: "memory")
; #define BAR __builtin_amdgcn_s_barrier()
; #define SCHED __builtin_amdgcn_sched_barrier(0)
; template <int EPI>
; __device__ __forceinline__ void gemm_tile(const Params& p, const bf16* __restrict__ A, const bf16* __restrict__ Bt, const int K,
;                                           const int nt, const int brow, const int bcol, int pm, int pn) {
;     ...
;     STAGE(SB(0, 1), Bt, bcol + HALF, t + 2);
;     WAIT_V(6); BAR; MMA(1, 1, At, B1); BAR;
;     LDB(B0, 1, 0); SCHED; LDA(At, 1, 0); STAGE(SA(0, 1), A, brow + HALF, t + 2);
;     WAIT_L(8); BAR; WAIT_L(0); MMA(0, 0, At, B0); BAR; SCHED;
;     LDB(B1, 1, 1); STAGE(SB(1, 0), Bt, bcol, t + 3);
;     BAR; WAIT_L(0); MMA(0, 1, At, B1); BAR;
	s_setprio 0
	s_add_i32 s88, s88, 2
	s_add_u32 s68, s68, 0x100
	s_addc_u32 s69, s69, 0
	s_add_u32 s70, s70, 0x100
	s_addc_u32 s71, s71, 0
	s_mov_b64 s[84:85], 0x4d60100
	v_lshl_add_u64 v[158:159], v[228:229], 0, s[84:85]
	v_readfirstlane_b32 s84, v140
	s_mov_b32 m0, s84
	s_mov_b64 s[84:85], 0x4e10100
	global_load_lds_dwordx4 v[158:159], off
	v_lshl_add_u64 v[158:159], v[228:229], 0, s[84:85]
	v_readfirstlane_b32 s84, v141
	s_mov_b32 m0, s84
	s_nop 0
	global_load_lds_dwordx4 v[158:159], off
	s_mov_b64 s[84:85], 0x12662100
	v_lshl_add_u64 v[248:249], v[204:205], 0, s[84:85]
	s_mov_b64 s[84:85], 0x12712100
	v_lshl_add_u64 v[250:251], v[204:205], 0, s[84:85]
	s_waitcnt vmcnt(6)
	s_setprio 1
	s_barrier
	v_mfma_f32_16x16x32_bf16 v[28:31], v[174:177], v[212:215], v[28:31]
	v_mfma_f32_16x16x32_bf16 v[24:27], v[174:177], v[220:223], v[24:27]
	v_mfma_f32_16x16x32_bf16 v[20:23], v[182:185], v[212:215], v[20:23]
	v_mfma_f32_16x16x32_bf16 v[16:19], v[182:185], v[220:223], v[16:19]
	v_mfma_f32_16x16x32_bf16 v[12:15], v[190:193], v[212:215], v[12:15]
	v_mfma_f32_16x16x32_bf16 v[8:11], v[190:193], v[220:223], v[8:11]
	v_mfma_f32_16x16x32_bf16 v[4:7], v[200:203], v[212:215], v[4:7]
	v_mfma_f32_16x16x32_bf16 v[0:3], v[200:203], v[220:223], v[0:3]
	v_mfma_f32_16x16x32_bf16 v[28:31], v[178:181], v[216:219], v[28:31]
	v_mfma_f32_16x16x32_bf16 v[24:27], v[178:181], v[224:227], v[24:27]
	v_mfma_f32_16x16x32_bf16 v[20:23], v[186:189], v[216:219], v[20:23]
	v_mfma_f32_16x16x32_bf16 v[16:19], v[186:189], v[224:227], v[16:19]
	v_mfma_f32_16x16x32_bf16 v[12:15], v[196:199], v[216:219], v[12:15]
	v_mfma_f32_16x16x32_bf16 v[8:11], v[196:199], v[224:227], v[8:11]
	v_mfma_f32_16x16x32_bf16 v[4:7], v[208:211], v[216:219], v[4:7]
	v_mfma_f32_16x16x32_bf16 v[0:3], v[208:211], v[224:227], v[0:3]
	s_barrier
	s_setprio 0
	ds_read_b128 v[158:161], v145
	ds_read_b128 v[162:165], v145 offset:1024
	ds_read_b128 v[166:169], v145 offset:2048
	ds_read_b128 v[170:173], v145 offset:3072
	s_mov_b32 m0, s100
	ds_read_b128 v[174:177], v137 offset:32768
	ds_read_b128 v[178:181], v137 offset:33792
	ds_read_b128 v[182:185], v136 offset:32768
	ds_read_b128 v[186:189], v136 offset:33792
	ds_read_b128 v[190:193], v135 offset:32768
	ds_read_b128 v[196:199], v135 offset:33792
	ds_read_b128 v[200:203], v133 offset:32768
	ds_read_b128 v[208:211], v133 offset:33792
	global_load_lds_dwordx4 v[248:249], off
	s_mov_b32 m0, s101
	s_nop 0
	global_load_lds_dwordx4 v[250:251], off
	s_waitcnt lgkmcnt(8)
	s_setprio 1
	s_barrier
	s_waitcnt lgkmcnt(0)
	v_mfma_f32_16x16x32_bf16 v[124:127], v[174:177], v[158:161], v[124:127]
	v_mfma_f32_16x16x32_bf16 v[120:123], v[174:177], v[166:169], v[120:123]
	v_mfma_f32_16x16x32_bf16 v[116:119], v[182:185], v[158:161], v[116:119]
	v_mfma_f32_16x16x32_bf16 v[112:115], v[182:185], v[166:169], v[112:115]
	v_mfma_f32_16x16x32_bf16 v[108:111], v[190:193], v[158:161], v[108:111]
	v_mfma_f32_16x16x32_bf16 v[104:107], v[190:193], v[166:169], v[104:107]
	v_mfma_f32_16x16x32_bf16 v[100:103], v[200:203], v[158:161], v[100:103]
	v_mfma_f32_16x16x32_bf16 v[96:99], v[200:203], v[166:169], v[96:99]
	v_mfma_f32_16x16x32_bf16 v[124:127], v[178:181], v[162:165], v[124:127]
	v_mfma_f32_16x16x32_bf16 v[120:123], v[178:181], v[170:173], v[120:123]
	v_mfma_f32_16x16x32_bf16 v[116:119], v[186:189], v[162:165], v[116:119]
	v_mfma_f32_16x16x32_bf16 v[112:115], v[186:189], v[170:173], v[112:115]
	v_mfma_f32_16x16x32_bf16 v[108:111], v[196:199], v[162:165], v[108:111]
	v_mfma_f32_16x16x32_bf16 v[104:107], v[196:199], v[170:173], v[104:107]
	v_mfma_f32_16x16x32_bf16 v[100:103], v[208:211], v[162:165], v[100:103]
	v_mfma_f32_16x16x32_bf16 v[96:99], v[208:211], v[170:173], v[96:99]
	s_barrier
	s_setprio 0
	s_mov_b64 s[84:85], 0x4c00180
	v_lshl_add_u64 v[230:231], v[228:229], 0, s[84:85]
	v_readfirstlane_b32 s84, v146
	s_mov_b32 m0, s84
	v_readfirstlane_b32 s84, v147
	ds_read_b128 v[212:215], v142
	ds_read_b128 v[216:219], v142 offset:1024
	ds_read_b128 v[220:223], v142 offset:2048
	ds_read_b128 v[224:227], v142 offset:3072
	global_load_lds_dwordx4 v[230:231], off
	v_lshl_add_u64 v[230:231], v[228:229], 0, s[10:11]
	s_mov_b32 m0, s84
	s_nop 0
	global_load_lds_dwordx4 v[230:231], off
	v_lshl_add_u64 v[252:253], v[204:205], 0, s[12:13]
	v_lshl_add_u64 v[230:231], v[204:205], 0, s[12:13]
	v_lshl_add_u64 v[254:255], v[204:205], 0, s[14:15]
	v_lshl_add_u64 v[204:205], v[204:205], 0, s[14:15]
	v_readfirstlane_b32 s84, v148
	s_mov_b32 m0, s84
	v_readfirstlane_b32 s85, v149
	s_setprio 1
	s_barrier
	s_waitcnt lgkmcnt(0)
	v_mfma_f32_16x16x32_bf16 v[92:95], v[174:177], v[212:215], v[92:95]
	v_mfma_f32_16x16x32_bf16 v[88:91], v[174:177], v[220:223], v[88:91]
	v_mfma_f32_16x16x32_bf16 v[84:87], v[182:185], v[212:215], v[84:87]
	v_mfma_f32_16x16x32_bf16 v[80:83], v[182:185], v[220:223], v[80:83]
	v_mfma_f32_16x16x32_bf16 v[76:79], v[190:193], v[212:215], v[76:79]
	v_mfma_f32_16x16x32_bf16 v[72:75], v[190:193], v[220:223], v[72:75]
	v_mfma_f32_16x16x32_bf16 v[68:71], v[200:203], v[212:215], v[68:71]
	v_mfma_f32_16x16x32_bf16 v[64:67], v[200:203], v[220:223], v[64:67]
	v_mfma_f32_16x16x32_bf16 v[92:95], v[178:181], v[216:219], v[92:95]
	v_mfma_f32_16x16x32_bf16 v[88:91], v[178:181], v[224:227], v[88:91]
	v_mfma_f32_16x16x32_bf16 v[84:87], v[186:189], v[216:219], v[84:87]
	v_mfma_f32_16x16x32_bf16 v[80:83], v[186:189], v[224:227], v[80:83]
	v_mfma_f32_16x16x32_bf16 v[76:79], v[196:199], v[216:219], v[76:79]
	v_mfma_f32_16x16x32_bf16 v[72:75], v[196:199], v[224:227], v[72:75]
	v_mfma_f32_16x16x32_bf16 v[68:71], v[208:211], v[216:219], v[68:71]
	v_mfma_f32_16x16x32_bf16 v[64:67], v[208:211], v[224:227], v[64:67]
	s_barrier
; #define WAIT_V(n) asm volatile("s_waitcnt vmcnt(" #n ")" ::: "memory")
; #define WAIT_L(n) asm volatile("s_waitcnt lgkmcnt(" #n ")" ::: "memory")
; #define BAR __builtin_amdgcn_s_barrier()
; #define SCHED __builtin_amdgcn_sched_barrier(0)
; template <int EPI>
; __device__ __forceinline__ void gemm_tile(const Params& p, const bf16* __restrict__ A, const bf16* __restrict__ Bt, const int K,
;                                           const int nt, const int brow, const int bcol, int pm, int pn) {
;     ...
;     LDA(At, 1, 1); STAGE(SA(1, 0), A, brow, t + 3);
;     BAR; WAIT_L(0); MMA(1, 0, At, B0); BAR; SCHED;
;     STAGE(SB(1, 1), Bt, bcol + HALF, t + 3);
;     WAIT_V(6); BAR; MMA(1, 1, At, B1); BAR;
;   }
;   { LDB(B0, 0, 0); LDA(At, 0, 0); STAGE(SA(1, 1), A, brow + HALF, nt - 1);
;     BAR; WAIT_L(0); MMA(0, 0, At, B0); BAR;
	s_setprio 0
	ds_read_b128 v[174:177], v137 offset:49152
	ds_read_b128 v[178:181], v137 offset:50176
	ds_read_b128 v[182:185], v136 offset:49152
	ds_read_b128 v[186:189], v136 offset:50176
	ds_read_b128 v[190:193], v135 offset:49152
	ds_read_b128 v[196:199], v135 offset:50176
	ds_read_b128 v[200:203], v133 offset:49152
	ds_read_b128 v[208:211], v133 offset:50176
	global_load_lds_dwordx4 v[252:253], off
	s_mov_b32 m0, s85
	s_nop 0
	global_load_lds_dwordx4 v[254:255], off
	s_setprio 1
	s_barrier
	s_waitcnt lgkmcnt(0)
	v_mfma_f32_16x16x32_bf16 v[60:63], v[174:177], v[158:161], v[60:63]
	v_mfma_f32_16x16x32_bf16 v[56:59], v[174:177], v[166:169], v[56:59]
	v_mfma_f32_16x16x32_bf16 v[52:55], v[182:185], v[158:161], v[52:55]
	v_mfma_f32_16x16x32_bf16 v[48:51], v[182:185], v[166:169], v[48:51]
	v_mfma_f32_16x16x32_bf16 v[44:47], v[190:193], v[158:161], v[44:47]
	v_mfma_f32_16x16x32_bf16 v[40:43], v[190:193], v[166:169], v[40:43]
	v_mfma_f32_16x16x32_bf16 v[36:39], v[200:203], v[158:161], v[36:39]
	v_mfma_f32_16x16x32_bf16 v[32:35], v[200:203], v[166:169], v[32:35]
	v_mfma_f32_16x16x32_bf16 v[60:63], v[178:181], v[162:165], v[60:63]
	v_mfma_f32_16x16x32_bf16 v[56:59], v[178:181], v[170:173], v[56:59]
	v_mfma_f32_16x16x32_bf16 v[52:55], v[186:189], v[162:165], v[52:55]
	v_mfma_f32_16x16x32_bf16 v[48:51], v[186:189], v[170:173], v[48:51]
	v_mfma_f32_16x16x32_bf16 v[44:47], v[196:199], v[162:165], v[44:47]
	v_mfma_f32_16x16x32_bf16 v[40:43], v[196:199], v[170:173], v[40:43]
	v_mfma_f32_16x16x32_bf16 v[36:39], v[208:211], v[162:165], v[36:39]
	v_mfma_f32_16x16x32_bf16 v[32:35], v[208:211], v[170:173], v[32:35]
	s_barrier
	s_setprio 0
	v_readfirstlane_b32 s84, v150
	v_lshl_add_u64 v[158:159], v[228:229], 0, s[16:17]
	s_mov_b32 m0, s84
	v_readfirstlane_b32 s84, v152
	global_load_lds_dwordx4 v[158:159], off
	v_lshl_add_u64 v[158:159], v[228:229], 0, s[18:19]
	s_mov_b32 m0, s84
	s_nop 0
	global_load_lds_dwordx4 v[158:159], off
	v_lshl_add_u64 v[204:205], s[70:71], 0, v[130:131]
	s_mov_b64 s[84:85], 0x12662080
	v_lshl_add_u64 v[246:247], v[204:205], 0, s[84:85]
	s_mov_b64 s[84:85], 0x12712080
	v_lshl_add_u64 v[244:245], v[204:205], 0, s[84:85]
	s_waitcnt vmcnt(6)
	s_setprio 1
	s_barrier
	v_mfma_f32_16x16x32_bf16 v[28:31], v[174:177], v[212:215], v[28:31]
	v_mfma_f32_16x16x32_bf16 v[24:27], v[174:177], v[220:223], v[24:27]
	v_mfma_f32_16x16x32_bf16 v[20:23], v[182:185], v[212:215], v[20:23]
	v_mfma_f32_16x16x32_bf16 v[16:19], v[182:185], v[220:223], v[16:19]
	v_mfma_f32_16x16x32_bf16 v[12:15], v[190:193], v[212:215], v[12:15]
	v_mfma_f32_16x16x32_bf16 v[8:11], v[190:193], v[220:223], v[8:11]
	v_mfma_f32_16x16x32_bf16 v[4:7], v[200:203], v[212:215], v[4:7]
	v_mfma_f32_16x16x32_bf16 v[0:3], v[200:203], v[220:223], v[0:3]
	v_mfma_f32_16x16x32_bf16 v[28:31], v[178:181], v[216:219], v[28:31]
	v_mfma_f32_16x16x32_bf16 v[24:27], v[178:181], v[224:227], v[24:27]
	v_mfma_f32_16x16x32_bf16 v[20:23], v[186:189], v[216:219], v[20:23]
	v_mfma_f32_16x16x32_bf16 v[16:19], v[186:189], v[224:227], v[16:19]
	v_mfma_f32_16x16x32_bf16 v[12:15], v[196:199], v[216:219], v[12:15]
	v_mfma_f32_16x16x32_bf16 v[8:11], v[196:199], v[224:227], v[8:11]
	v_mfma_f32_16x16x32_bf16 v[4:7], v[208:211], v[216:219], v[4:7]
	v_mfma_f32_16x16x32_bf16 v[0:3], v[208:211], v[224:227], v[0:3]
	s_barrier
	s_setprio 0
	s_cmpk_lt_u32 s88, 0x54
	s_cbranch_scc1 .LBB0_1704
	s_add_u32 s68, s62, s87
	s_addc_u32 s69, s63, s86
	v_lshl_add_u64 v[130:131], s[68:69], 0, v[128:129]
	v_readfirstlane_b32 s68, v154
	s_mov_b32 m0, s68
	s_add_u32 s68, s62, s79
	v_lshl_add_u64 v[130:131], v[130:131], 0, s[20:21]
	s_addc_u32 s69, s63, s78
	ds_read_b128 v[138:141], v155
	ds_read_b128 v[146:149], v155 offset:1024
	ds_read_b128 v[158:161], v155 offset:2048
	ds_read_b128 v[162:165], v155 offset:3072
	ds_read_b128 v[166:169], v137
	ds_read_b128 v[170:173], v137 offset:1024
	ds_read_b128 v[174:177], v136
	ds_read_b128 v[178:181], v136 offset:1024
	ds_read_b128 v[182:185], v135
	ds_read_b128 v[186:189], v135 offset:1024
	ds_read_b128 v[190:193], v133
	ds_read_b128 v[196:199], v133 offset:1024
	global_load_lds_dwordx4 v[130:131], off
	v_lshl_add_u64 v[130:131], s[68:69], 0, v[128:129]
	v_readfirstlane_b32 s68, v153
	v_lshl_add_u64 v[130:131], v[130:131], 0, s[20:21]
	s_mov_b32 m0, s68
	s_nop 0
	global_load_lds_dwordx4 v[130:131], off
	s_setprio 1
	s_barrier
	s_waitcnt lgkmcnt(0)
	v_mfma_f32_16x16x32_bf16 v[124:127], v[166:169], v[138:141], v[124:127]
	v_mfma_f32_16x16x32_bf16 v[120:123], v[166:169], v[158:161], v[120:123]
	v_mfma_f32_16x16x32_bf16 v[116:119], v[174:177], v[138:141], v[116:119]
	v_mfma_f32_16x16x32_bf16 v[108:111], v[182:185], v[138:141], v[108:111]
	v_mfma_f32_16x16x32_bf16 v[124:127], v[170:173], v[146:149], v[124:127]
	v_mfma_f32_16x16x32_bf16 v[120:123], v[170:173], v[162:165], v[120:123]
	v_mfma_f32_16x16x32_bf16 v[116:119], v[178:181], v[146:149], v[116:119]
	v_mfma_f32_16x16x32_bf16 v[112:115], v[174:177], v[158:161], v[112:115]
	v_mfma_f32_16x16x32_bf16 v[108:111], v[186:189], v[146:149], v[108:111]
	v_mfma_f32_16x16x32_bf16 v[104:107], v[182:185], v[158:161], v[104:107]
	v_mfma_f32_16x16x32_bf16 v[100:103], v[190:193], v[138:141], v[100:103]
	v_mfma_f32_16x16x32_bf16 v[96:99], v[190:193], v[158:161], v[96:99]
	v_mfma_f32_16x16x32_bf16 v[152:155], v[178:181], v[162:165], v[112:115]
	v_mfma_f32_16x16x32_bf16 v[200:203], v[186:189], v[162:165], v[104:107]
	v_mfma_f32_16x16x32_bf16 v[208:211], v[196:199], v[146:149], v[100:103]
	v_mfma_f32_16x16x32_bf16 v[212:215], v[196:199], v[162:165], v[96:99]
	s_barrier
; #define WAIT_V(n) asm volatile("s_waitcnt vmcnt(" #n ")" ::: "memory")
; #define WAIT_L(n) asm volatile("s_waitcnt lgkmcnt(" #n ")" ::: "memory")
; #define BAR __builtin_amdgcn_s_barrier()
; template <int EPI>
; __device__ __forceinline__ void gemm_tile(const Params& p, const bf16* __restrict__ A, const bf16* __restrict__ Bt, const int K,
;                                           const int nt, const int brow, const int bcol, int pm, int pn) {
;     ...
;     LDB(B1, 0, 1); BAR; WAIT_L(0); MMA(0, 1, At, B1); BAR;
;     LDA(At, 0, 1); WAIT_V(4); BAR; WAIT_L(0); MMA(1, 0, At, B0); MMA(1, 1, At, B1); BAR; }
;   { LDB(B0, 1, 0); LDA(At, 1, 0); WAIT_V(2); BAR; WAIT_L(0); MMA(0, 0, At, B0); BAR;
	s_setprio 0
	s_nop 1
	ds_read_b128 v[96:99], v151
	ds_read_b128 v[100:103], v151 offset:1024
	ds_read_b128 v[104:107], v151 offset:2048
	ds_read_b128 v[112:115], v151 offset:3072
	s_setprio 1
	s_barrier
	s_waitcnt lgkmcnt(0)
	v_mfma_f32_16x16x32_bf16 v[92:95], v[166:169], v[96:99], v[92:95]
	v_mfma_f32_16x16x32_bf16 v[88:91], v[166:169], v[104:107], v[88:91]
	v_mfma_f32_16x16x32_bf16 v[84:87], v[174:177], v[96:99], v[84:87]
	v_mfma_f32_16x16x32_bf16 v[76:79], v[182:185], v[96:99], v[76:79]
	v_mfma_f32_16x16x32_bf16 v[92:95], v[170:173], v[100:103], v[92:95]
	v_mfma_f32_16x16x32_bf16 v[88:91], v[170:173], v[112:115], v[88:91]
	v_mfma_f32_16x16x32_bf16 v[84:87], v[178:181], v[100:103], v[84:87]
	v_mfma_f32_16x16x32_bf16 v[80:83], v[174:177], v[104:107], v[80:83]
	v_mfma_f32_16x16x32_bf16 v[76:79], v[186:189], v[100:103], v[76:79]
	v_mfma_f32_16x16x32_bf16 v[72:75], v[182:185], v[104:107], v[72:75]
	v_mfma_f32_16x16x32_bf16 v[68:71], v[190:193], v[96:99], v[68:71]
	v_mfma_f32_16x16x32_bf16 v[64:67], v[190:193], v[104:107], v[64:67]
	v_mfma_f32_16x16x32_bf16 v[166:169], v[178:181], v[112:115], v[80:83]
	v_mfma_f32_16x16x32_bf16 v[170:173], v[186:189], v[112:115], v[72:75]
	v_mfma_f32_16x16x32_bf16 v[174:177], v[196:199], v[100:103], v[68:71]
	v_mfma_f32_16x16x32_bf16 v[178:181], v[196:199], v[112:115], v[64:67]
	s_barrier
	s_setprio 0
	s_nop 1
	ds_read_b128 v[64:67], v137 offset:16384
	ds_read_b128 v[68:71], v137 offset:17408
	ds_read_b128 v[72:75], v136 offset:16384
	ds_read_b128 v[80:83], v136 offset:17408
	ds_read_b128 v[182:185], v135 offset:16384
	ds_read_b128 v[186:189], v135 offset:17408
	ds_read_b128 v[190:193], v133 offset:16384
	ds_read_b128 v[196:199], v133 offset:17408
	s_waitcnt vmcnt(4)
	s_setprio 1
	s_barrier
	s_waitcnt lgkmcnt(0)
	v_mfma_f32_16x16x32_bf16 v[60:63], v[64:67], v[138:141], v[60:63]
	v_mfma_f32_16x16x32_bf16 v[56:59], v[64:67], v[158:161], v[56:59]
	v_mfma_f32_16x16x32_bf16 v[52:55], v[72:75], v[138:141], v[52:55]
	v_mfma_f32_16x16x32_bf16 v[44:47], v[182:185], v[138:141], v[44:47]
	v_mfma_f32_16x16x32_bf16 v[60:63], v[68:71], v[146:149], v[60:63]
	v_mfma_f32_16x16x32_bf16 v[56:59], v[68:71], v[162:165], v[56:59]
	v_mfma_f32_16x16x32_bf16 v[52:55], v[80:83], v[146:149], v[52:55]
	v_mfma_f32_16x16x32_bf16 v[48:51], v[72:75], v[158:161], v[48:51]
	v_mfma_f32_16x16x32_bf16 v[44:47], v[186:189], v[146:149], v[44:47]
	v_mfma_f32_16x16x32_bf16 v[40:43], v[182:185], v[158:161], v[40:43]
	v_mfma_f32_16x16x32_bf16 v[36:39], v[190:193], v[138:141], v[36:39]
	v_mfma_f32_16x16x32_bf16 v[32:35], v[190:193], v[158:161], v[32:35]
	v_mfma_f32_16x16x32_bf16 v[216:219], v[80:83], v[162:165], v[48:51]
	v_mfma_f32_16x16x32_bf16 v[220:223], v[186:189], v[162:165], v[40:43]
	v_mfma_f32_16x16x32_bf16 v[138:141], v[196:199], v[146:149], v[36:39]
	v_mfma_f32_16x16x32_bf16 v[146:149], v[196:199], v[162:165], v[32:35]
	s_setprio 0
	s_setprio 1
	v_mfma_f32_16x16x32_bf16 v[28:31], v[64:67], v[96:99], v[28:31]
	v_mfma_f32_16x16x32_bf16 v[24:27], v[64:67], v[104:107], v[24:27]
	v_mfma_f32_16x16x32_bf16 v[20:23], v[72:75], v[96:99], v[20:23]
	v_mfma_f32_16x16x32_bf16 v[12:15], v[182:185], v[96:99], v[12:15]
	v_mfma_f32_16x16x32_bf16 v[28:31], v[68:71], v[100:103], v[28:31]
	v_mfma_f32_16x16x32_bf16 v[24:27], v[68:71], v[112:115], v[24:27]
	v_mfma_f32_16x16x32_bf16 v[20:23], v[80:83], v[100:103], v[20:23]
	v_mfma_f32_16x16x32_bf16 v[16:19], v[72:75], v[104:107], v[16:19]
	v_mfma_f32_16x16x32_bf16 v[12:15], v[186:189], v[100:103], v[12:15]
	v_mfma_f32_16x16x32_bf16 v[8:11], v[182:185], v[104:107], v[8:11]
	v_mfma_f32_16x16x32_bf16 v[4:7], v[190:193], v[96:99], v[4:7]
	v_mfma_f32_16x16x32_bf16 v[0:3], v[190:193], v[104:107], v[0:3]
	v_mfma_f32_16x16x32_bf16 v[158:161], v[80:83], v[112:115], v[16:19]
	v_mfma_f32_16x16x32_bf16 v[162:165], v[186:189], v[112:115], v[8:11]
	v_mfma_f32_16x16x32_bf16 v[182:185], v[196:199], v[100:103], v[4:7]
	v_mfma_f32_16x16x32_bf16 v[186:189], v[196:199], v[112:115], v[0:3]
	s_barrier
	s_setprio 0
	s_nop 1
	ds_read_b128 v[0:3], v145
	ds_read_b128 v[4:7], v145 offset:1024
	ds_read_b128 v[8:11], v145 offset:2048
	ds_read_b128 v[16:19], v145 offset:3072
	ds_read_b128 v[32:35], v137 offset:32768
	ds_read_b128 v[36:39], v137 offset:33792
	ds_read_b128 v[40:43], v136 offset:32768
	ds_read_b128 v[48:51], v136 offset:33792
	ds_read_b128 v[190:193], v135 offset:32768
	ds_read_b128 v[196:199], v135 offset:33792
	ds_read_b128 v[224:227], v133 offset:32768
	ds_read_b128 v[228:231], v133 offset:33792
	s_waitcnt vmcnt(2)
	s_setprio 1
	s_barrier
; #define WAIT_V(n) asm volatile("s_waitcnt vmcnt(" #n ")" ::: "memory")
; #define WAIT_L(n) asm volatile("s_waitcnt lgkmcnt(" #n ")" ::: "memory")
; #define BAR __builtin_amdgcn_s_barrier()
; template <int EPI>
; __device__ __forceinline__ void gemm_tile(const Params& p, const bf16* __restrict__ A, const bf16* __restrict__ Bt, const int K,
;                                           const int nt, const int brow, const int bcol, int pm, int pn) {
;     ...
;   { LDB(B0, 1, 0); LDA(At, 1, 0); WAIT_V(2); BAR; WAIT_L(0); MMA(0, 0, At, B0); BAR;
;     LDB(B1, 1, 1); WAIT_V(0); BAR; WAIT_L(0); MMA(0, 1, At, B1); BAR;
;     LDA(At, 1, 1); BAR; WAIT_L(0); MMA(1, 0, At, B0); MMA(1, 1, At, B1); BAR; }
;   if (wr == 0) BAR;
	s_waitcnt lgkmcnt(0)
	v_mfma_f32_16x16x32_bf16 v[64:67], v[32:35], v[0:3], v[124:127]
	v_mfma_f32_16x16x32_bf16 v[96:99], v[36:39], v[4:7], v[64:67]
	v_mfma_f32_16x16x32_bf16 v[64:67], v[32:35], v[8:11], v[120:123]
	v_mfma_f32_16x16x32_bf16 v[112:115], v[36:39], v[16:19], v[64:67]
	v_mfma_f32_16x16x32_bf16 v[64:67], v[40:43], v[0:3], v[116:119]
	v_mfma_f32_16x16x32_bf16 v[100:103], v[48:51], v[4:7], v[64:67]
	v_mfma_f32_16x16x32_bf16 v[64:67], v[40:43], v[8:11], v[152:155]
	v_mfma_f32_16x16x32_bf16 v[116:119], v[48:51], v[16:19], v[64:67]
	v_mfma_f32_16x16x32_bf16 v[64:67], v[190:193], v[0:3], v[108:111]
	v_mfma_f32_16x16x32_bf16 v[104:107], v[196:199], v[4:7], v[64:67]
	v_mfma_f32_16x16x32_bf16 v[64:67], v[190:193], v[8:11], v[200:203]
	v_mfma_f32_16x16x32_bf16 v[120:123], v[196:199], v[16:19], v[64:67]
	v_mfma_f32_16x16x32_bf16 v[64:67], v[224:227], v[0:3], v[208:211]
	v_mfma_f32_16x16x32_bf16 v[108:111], v[228:231], v[4:7], v[64:67]
	v_mfma_f32_16x16x32_bf16 v[64:67], v[224:227], v[8:11], v[212:215]
	v_mfma_f32_16x16x32_bf16 v[124:127], v[228:231], v[16:19], v[64:67]
	s_barrier
	s_setprio 0
	ds_read_b128 v[150:153], v142
	ds_read_b128 v[200:203], v142 offset:1024
	ds_read_b128 v[208:211], v142 offset:2048
	ds_read_b128 v[142:145], v142 offset:3072
	s_waitcnt vmcnt(0)
	s_setprio 1
	s_barrier
	s_waitcnt lgkmcnt(0)
	v_mfma_f32_16x16x32_bf16 v[64:67], v[32:35], v[150:153], v[92:95]
	v_mfma_f32_16x16x32_bf16 v[32:35], v[32:35], v[208:211], v[88:91]
	v_mfma_f32_16x16x32_bf16 v[80:83], v[36:39], v[142:145], v[32:35]
	v_mfma_f32_16x16x32_bf16 v[32:35], v[40:43], v[150:153], v[84:87]
	v_mfma_f32_16x16x32_bf16 v[68:71], v[48:51], v[200:203], v[32:35]
	v_mfma_f32_16x16x32_bf16 v[32:35], v[40:43], v[208:211], v[166:169]
	v_mfma_f32_16x16x32_bf16 v[84:87], v[48:51], v[142:145], v[32:35]
	v_mfma_f32_16x16x32_bf16 v[32:35], v[190:193], v[150:153], v[76:79]
	v_mfma_f32_16x16x32_bf16 v[72:75], v[196:199], v[200:203], v[32:35]
	v_mfma_f32_16x16x32_bf16 v[32:35], v[190:193], v[208:211], v[170:173]
	v_mfma_f32_16x16x32_bf16 v[88:91], v[196:199], v[142:145], v[32:35]
	v_mfma_f32_16x16x32_bf16 v[32:35], v[224:227], v[150:153], v[174:177]
	v_mfma_f32_16x16x32_bf16 v[76:79], v[228:231], v[200:203], v[32:35]
	v_mfma_f32_16x16x32_bf16 v[32:35], v[224:227], v[208:211], v[178:181]
	v_mfma_f32_16x16x32_bf16 v[64:67], v[36:39], v[200:203], v[64:67]
	v_mfma_f32_16x16x32_bf16 v[92:95], v[228:231], v[142:145], v[32:35]
	s_barrier
	s_setprio 0
	ds_read_b128 v[166:169], v137 offset:49152
	ds_read_b128 v[170:173], v137 offset:50176
	ds_read_b128 v[174:177], v136 offset:49152
	ds_read_b128 v[178:181], v136 offset:50176
	ds_read_b128 v[190:193], v135 offset:49152
	ds_read_b128 v[134:137], v135 offset:50176
	ds_read_b128 v[196:199], v133 offset:49152
	ds_read_b128 v[130:133], v133 offset:50176
	s_setprio 1
	s_barrier
	s_waitcnt lgkmcnt(0)
	v_mfma_f32_16x16x32_bf16 v[36:39], v[166:169], v[8:11], v[56:59]
	v_mfma_f32_16x16x32_bf16 v[40:43], v[174:177], v[8:11], v[216:219]
	v_mfma_f32_16x16x32_bf16 v[32:35], v[166:169], v[0:3], v[60:63]
	v_mfma_f32_16x16x32_bf16 v[48:51], v[170:173], v[16:19], v[36:39]
	v_mfma_f32_16x16x32_bf16 v[36:39], v[174:177], v[0:3], v[52:55]
	v_mfma_f32_16x16x32_bf16 v[52:55], v[178:181], v[16:19], v[40:43]
	v_mfma_f32_16x16x32_bf16 v[40:43], v[190:193], v[0:3], v[44:47]
	v_mfma_f32_16x16x32_bf16 v[44:47], v[190:193], v[8:11], v[220:223]
	v_mfma_f32_16x16x32_bf16 v[0:3], v[196:199], v[0:3], v[138:141]
	v_mfma_f32_16x16x32_bf16 v[56:59], v[134:137], v[16:19], v[44:47]
	v_mfma_f32_16x16x32_bf16 v[44:47], v[130:133], v[4:7], v[0:3]
	v_mfma_f32_16x16x32_bf16 v[0:3], v[196:199], v[8:11], v[146:149]
	v_mfma_f32_16x16x32_bf16 v[32:35], v[170:173], v[4:7], v[32:35]
	v_mfma_f32_16x16x32_bf16 v[36:39], v[178:181], v[4:7], v[36:39]
	v_mfma_f32_16x16x32_bf16 v[40:43], v[134:137], v[4:7], v[40:43]
	v_mfma_f32_16x16x32_bf16 v[60:63], v[130:133], v[16:19], v[0:3]
	s_setprio 0
	s_setprio 1
	v_mfma_f32_16x16x32_bf16 v[4:7], v[166:169], v[208:211], v[24:27]
	v_mfma_f32_16x16x32_bf16 v[8:11], v[174:177], v[208:211], v[158:161]
	v_mfma_f32_16x16x32_bf16 v[16:19], v[170:173], v[142:145], v[4:7]
	v_mfma_f32_16x16x32_bf16 v[4:7], v[174:177], v[150:153], v[20:23]
	v_mfma_f32_16x16x32_bf16 v[20:23], v[178:181], v[142:145], v[8:11]
	v_mfma_f32_16x16x32_bf16 v[8:11], v[190:193], v[150:153], v[12:15]
	v_mfma_f32_16x16x32_bf16 v[12:15], v[190:193], v[208:211], v[162:165]
	v_mfma_f32_16x16x32_bf16 v[0:3], v[166:169], v[150:153], v[28:31]
	v_mfma_f32_16x16x32_bf16 v[24:27], v[134:137], v[142:145], v[12:15]
	v_mfma_f32_16x16x32_bf16 v[12:15], v[196:199], v[150:153], v[182:185]
	v_mfma_f32_16x16x32_bf16 v[28:31], v[196:199], v[208:211], v[186:189]
	v_mfma_f32_16x16x32_bf16 v[0:3], v[170:173], v[200:203], v[0:3]
	v_mfma_f32_16x16x32_bf16 v[4:7], v[178:181], v[200:203], v[4:7]
	v_mfma_f32_16x16x32_bf16 v[8:11], v[134:137], v[200:203], v[8:11]
	v_mfma_f32_16x16x32_bf16 v[12:15], v[130:133], v[200:203], v[12:15]
	v_mfma_f32_16x16x32_bf16 v[28:31], v[130:133], v[142:145], v[28:31]
	s_barrier
	s_setprio 0
	s_cmpk_gt_u32 s77, 0xff
	s_cbranch_scc1 .LBB0_1696
	s_barrier
	s_branch .LBB0_1696
